# static priority raise (s_setprio 2) for waves 4..7 during the attention units
# baseline (speedup 1.0000x reference)
;   #define PIN(x) asm volatile("":"+v"(x))
; template<int THRL> __device__ __forceinline__ void attn_unit(long rowbase,int qb,int t0,bool WIN,bool NOMAX,const bf16*Qc,const bf16*__restrict__ Kc,const bf16*__restrict__ Vc,bf16*Oc,float s2,float sink2,char*shm,
;     bf16x8 (&qr)[4],bool pref,const bf16*qkvb,int vn,int in_){
;   int tid=threadIdx.x; asm volatile("":"+v"(tid)); const int lane=tid&63,r32=lane&31,hi=lane>>5; const int wid=__builtin_amdgcn_readfirstlane(tid>>6);
;   const int q0=qb*QB;
;   const bf16*Qw=Qc+(rowbase+q0+wid*QBLK)*PIN;
;   const bf16*Kh=Kc+(rowbase+(long)t0*KVBLK)*PIN,*Vh=Vc+(rowbase+(long)t0*KVBLK)*PIN;
;   const unsigned lds0=(unsigned)(uintptr_t)shm;
;   float*wsf=(float*)(shm+LDS_WS)+wid*64;
;   const bf16*ksrc=Kh+(long)lane*PIN+wid*8;
;   const bf16*vsrc=Vh+(long)(16*(wid&3)+(lane>>2))*PIN+(wid>>2)*32+(lane&3)*8;
;   const unsigned kdst=lds0+LDS_K+wid*1024, vdst=lds0+LDS_V+wid*1024;
;     ...
;   const int vb0=(int)(lds0+LDS_V)+((lane>>4)&1)*32+(lane&3)*8+(4*hi+((lane&15)>>2))*64;
;   const char*Kbase=shm+LDS_K; bf16x8 kf[8];
;   const lds_cptr shm3=(lds_cptr)shm; const lds_cptr kp0=shm3+LDS_K+hi*1024+r32*16; const lds_cptr vp0=shm3+LDS_V+((lane>>4)&1)*32+(lane&3)*8+(4*hi+((lane&15)>>2))*64;
.LBB0_260:
	s_ashr_i32 s43, s42, 31
	s_lshl_b64 s[42:43], s[42:43], 13
	s_lshl_b32 s4, s39, 1
	s_add_u32 s39, s72, s4
	s_addc_u32 s50, s73, 0
	s_lshl_b32 s4, s38, 1
	v_mov_b32_e32 v50, v234
	s_add_u32 s51, s72, s4
	s_addc_u32 s60, s73, 0
	v_readfirstlane_b32 s44, v50
	s_ashr_i32 s80, s44, 6
	s_cmp_lt_u32 s80, 4
	s_cbranch_scc1 .Lmy_prio_skip
	s_setprio 2
.Lmy_prio_skip:
	s_lshl_b32 s4, s2, 8
	s_add_u32 s38, s42, s4
	s_addc_u32 s45, s43, 0
	s_lshl_b32 s2, s80, 5
	s_ashr_i32 s59, s2, 31
	s_add_u32 s58, s38, s2
	s_addc_u32 s59, s45, s59
	s_lshl_b32 s45, s48, 6
	s_add_u32 s38, s42, s45
	s_addc_u32 s42, s43, 0
	s_mulk_i32 s42, 0x1200
	s_mul_hi_u32 s43, s38, 0x1200
	s_add_i32 s43, s43, s42
	s_mul_i32 s42, s38, 0x1200
	s_add_u32 s38, s39, s42
	v_and_b32_e32 v183, 63, v50
	s_addc_u32 s39, s50, s43
	s_add_u32 s42, s51, s42
	v_mul_u32_u24_e32 v0, 0x900, v183
	s_addc_u32 s43, s60, s43
	v_lshlrev_b32_e32 v0, 1, v0
	s_lshl_b32 s60, s80, 3
	v_lshl_add_u64 v[2:3], s[38:39], 0, v[0:1]
	s_ashr_i32 s61, s60, 31
	v_lshl_add_u64 v[194:195], s[60:61], 1, v[2:3]
	s_lshl_b32 s38, s80, 4
	v_bfe_u32 v2, v50, 2, 4
	v_and_or_b32 v2, s38, 48, v2
	v_mul_u32_u24_e32 v2, 0x900, v2
	s_ashr_i32 s38, s44, 3
	v_lshlrev_b32_e32 v2, 1, v2
	v_mov_b32_e32 v3, v1
	s_andn2_b32 s38, s38, 31
	v_lshlrev_b32_e32 v233, 3, v50
	v_lshl_add_u64 v[2:3], s[42:43], 0, v[2:3]
	s_ashr_i32 s39, s38, 31
	v_and_b32_e32 v219, 24, v233
	s_lshl_b32 s82, s80, 10
	v_lshl_add_u64 v[2:3], s[38:39], 1, v[2:3]
	v_lshlrev_b32_e32 v4, 1, v219
	v_mov_b32_e32 v5, v1
	s_cmp_lg_u32 0, -1
	v_and_b32_e32 v180, 31, v50
	v_lshl_add_u64 v[82:83], v[2:3], 0, v[4:5]
	s_cselect_b32 s38, 0, 0
	v_cndmask_b32_e64 v2, 0, 1, s[40:41]
	s_add_i32 s50, s82, s38
	v_cmp_ne_u32_e64 s[38:39], 1, v2
	v_mul_u32_u24_e32 v2, 0x900, v180
	v_bfe_u32 v181, v50, 5, 1
	s_add_i32 s79, s50, 0x6000
	s_mov_b64 s[42:43], -1
	s_andn2_b64 vcc, exec, s[40:41]
	v_lshlrev_b32_e32 v222, 1, v2
	s_cbranch_vccz .LBB0_352
	s_andn2_b64 vcc, exec, s[42:43]
	s_cbranch_vccz .LBB0_353
